# M1 state items: sample-stream items (serialized state update) issued first among the state items, on top of v22
# speedup vs baseline: 1.0084x; 1.0036x over previous
; __device__ __forceinline__ int lane_id() { int t; asm volatile("v_mbcnt_lo_u32_b32 %0, -1, 0\n\tv_mbcnt_hi_u32_b32 %0, -1, %0" : "=&v"(t)); return t; }
; __device__ __forceinline__ LaItem la_decode(int li) {
;     LaItem it; it.mx = li / 1088; const int r = li - it.mx * 1088;
;     if (r < 1024) { it.smp = false; it.c = r >> 3; it.h = r & 7; it.s = 0; it.row0 = 64 * it.c; it.C = 64; it.pos0 = 64 * it.c; }
;     else { it.smp = true; it.s = (r - 1024) >> 3; it.h = r & 7; it.c = 0; it.row0 = TP + 16 * it.s; it.C = 16; it.pos0 = 1024; }
;     return it;
; __global__ void __launch_bounds__(512, 2) fwd_megakernel(Params P) {
;     ...
;           while (it < N_ATT_ITEMS + N_LA_ITEMS) {
;               unsigned nx = 0; if (wv == 0 && lane_id() == 0) nx = __hip_atomic_fetch_add(ctr, 1u, __ATOMIC_RELAXED, __HIP_MEMORY_SCOPE_AGENT);
;               if (it < N_ATT_ITEMS) attn_item(P, l, lds, it, wv); else la_state_item(P, l, lds, it - N_ATT_ITEMS, wv);
.LBB0_308:
	s_add_i32 s18, s20, 0xfffffde0
	s_add_i32 s0, s18, 0x400
	s_add_i32 s1, s18, 0x800
	s_cmp_lt_u32 s18, 64
	s_cselect_b32 s0, s0, s1
	s_add_i32 s1, s18, 0xffffff80
	s_cmp_lt_u32 s18, 0x80
	s_cselect_b32 s0, s0, s1
	s_add_i32 s1, s18, 0xffffffc0
	s_cmp_lt_u32 s18, 0x480
	s_cselect_b32 s18, s0, s1
	s_cmpk_gt_u32 s18, 0x43f
	s_cselect_b64 s[14:15], -1, 0
	s_cmpk_lt_u32 s18, 0x440
	s_cselect_b64 s[8:9], -1, 0
	s_and_b64 s[0:1], s[8:9], exec
	s_cselect_b32 s0, 0, 0xfffffbc0
	s_add_i32 s18, s0, s18
	s_cmpk_lt_u32 s18, 0x400
	s_cselect_b64 s[34:35], -1, 0
	s_cmpk_gt_u32 s18, 0x3ff
	s_mov_b64 s[0:1], -1
	s_cbranch_scc1 .LBB0_310
	s_lshr_b32 s22, s18, 3
	s_lshl_b32 s25, s22, 6
	s_mov_b64 s[0:1], 0
